# NSA attention passes: LDS stage writes of the next tile issued before the PV MFMA block, K fragment reads issued right after the barrier
# baseline (speedup 1.0000x reference)
.LBB0_885:
	v_exp_f32_e32 v112, v80
	v_exp_f32_e32 v80, v96
	v_exp_f32_e32 v113, v81
	v_exp_f32_e32 v81, v97
	v_exp_f32_e32 v114, v82
	v_exp_f32_e32 v82, v98
	v_exp_f32_e32 v115, v83
	v_exp_f32_e32 v83, v99
	v_exp_f32_e32 v116, v84
	v_exp_f32_e32 v84, v100
	v_exp_f32_e32 v117, v85
	v_exp_f32_e32 v85, v101
	v_exp_f32_e32 v118, v86
	v_exp_f32_e32 v86, v102
	v_exp_f32_e32 v119, v87
	v_exp_f32_e32 v87, v103
	v_exp_f32_e32 v120, v88
	v_exp_f32_e32 v88, v104
	v_exp_f32_e32 v121, v89
	v_exp_f32_e32 v89, v105
	v_exp_f32_e32 v122, v90
	v_exp_f32_e32 v90, v106
	v_exp_f32_e32 v123, v91
	v_exp_f32_e32 v91, v107
	v_exp_f32_e32 v124, v92
	v_exp_f32_e32 v92, v108
	v_exp_f32_e32 v125, v93
	v_exp_f32_e32 v93, v109
	v_exp_f32_e32 v126, v94
	v_exp_f32_e32 v94, v110
	v_exp_f32_e32 v127, v95
	v_exp_f32_e32 v95, v111
	s_mov_b64 s[16:17], -1
	v_add_f32_e32 v0, v112, v80
	v_add_f32_e32 v1, v113, v81
	v_add_f32_e32 v3, v114, v82
	v_add_f32_e32 v96, v115, v83
	v_cvt_pk_bf16_f32 v97, v114, v115
	v_add_f32_e32 v0, v0, v116
	v_add_f32_e32 v1, v1, v117
	v_add_f32_e32 v3, v3, v118
	v_add_f32_e32 v96, v96, v119
	v_cvt_pk_bf16_f32 v98, v116, v117
	v_add_f32_e32 v0, v0, v84
	v_add_f32_e32 v1, v1, v85
	v_add_f32_e32 v3, v3, v86
	v_add_f32_e32 v96, v96, v87
	v_cvt_pk_bf16_f32 v99, v118, v119
	v_add_f32_e32 v0, v0, v120
	v_add_f32_e32 v1, v1, v121
	v_add_f32_e32 v3, v3, v122
	v_add_f32_e32 v96, v96, v123
	v_cvt_pk_bf16_f32 v100, v120, v121
	v_add_f32_e32 v0, v0, v88
	v_add_f32_e32 v1, v1, v89
	v_add_f32_e32 v3, v3, v90
	v_add_f32_e32 v96, v96, v91
	v_cvt_pk_bf16_f32 v101, v122, v123
	v_add_f32_e32 v0, v0, v124
	v_add_f32_e32 v1, v1, v125
	v_add_f32_e32 v3, v3, v126
	v_add_f32_e32 v96, v96, v127
	v_cvt_pk_bf16_f32 v102, v124, v125
	v_add_f32_e32 v0, v0, v92
	v_add_f32_e32 v1, v1, v93
	v_add_f32_e32 v3, v3, v94
	v_add_f32_e32 v96, v96, v95
	v_cvt_pk_bf16_f32 v103, v126, v127
	v_add_f32_e32 v0, v0, v1
	v_add_f32_e32 v1, v3, v96
	v_cvt_pk_bf16_f32 v96, v112, v113
	v_add_f32_e32 v0, v0, v1
	v_cvt_pk_bf16_f32 v80, v80, v81
	v_add_f32_e32 v209, v209, v0
	v_cvt_pk_bf16_f32 v81, v82, v83
	v_cvt_pk_bf16_f32 v82, v84, v85
	v_cvt_pk_bf16_f32 v83, v86, v87
	v_cvt_pk_bf16_f32 v84, v88, v89
	v_cvt_pk_bf16_f32 v85, v90, v91
	v_cvt_pk_bf16_f32 v86, v92, v93
	v_cvt_pk_bf16_f32 v87, v94, v95
	s_waitcnt vmcnt(1)
	ds_write_b128 v192, v[156:159] offset:9216
	s_waitcnt vmcnt(0)
	ds_write_b128 v194, v[160:163] offset:30720
	s_setprio 1
	v_mfma_f32_32x32x16_bf16 v[32:47], v[4:7], v[96:99], v[32:47]
	s_waitcnt lgkmcnt(12)
	v_mfma_f32_32x32x16_bf16 v[16:31], v[8:11], v[96:99], v[16:31]
	s_waitcnt lgkmcnt(10)
	v_mfma_f32_32x32x16_bf16 v[32:47], v[12:15], v[100:103], v[32:47]
	s_waitcnt lgkmcnt(8)
	v_mfma_f32_32x32x16_bf16 v[16:31], v[164:167], v[100:103], v[16:31]
	s_waitcnt lgkmcnt(6)
	v_mfma_f32_32x32x16_bf16 v[32:47], v[168:171], v[80:83], v[32:47]
	s_waitcnt lgkmcnt(4)
	v_mfma_f32_32x32x16_bf16 v[16:31], v[172:175], v[80:83], v[16:31]
	s_waitcnt lgkmcnt(2)
	v_mfma_f32_32x32x16_bf16 v[32:47], v[176:179], v[84:87], v[32:47]
	s_waitcnt lgkmcnt(0)
	v_mfma_f32_32x32x16_bf16 v[16:31], v[180:183], v[84:87], v[16:31]
	s_setprio 0
	s_cmp_lt_i32 s56, 0
	s_cbranch_scc1 .LBB0_900
	s_lshl_b64 s[16:17], 1, s69
	s_andn2_b64 s[58:59], s[12:13], s[16:17]
	s_ff1_i32_b64 s2, s[58:59]
	s_cmp_lg_u64 s[58:59], 0
	s_cselect_b32 s0, s2, -1
	s_cmp_lt_i32 s0, 0
	s_waitcnt lgkmcnt(0)
	s_barrier
	s_cbranch_scc1 .LBB0_888
	s_lshl_b64 s[12:13], s[0:1], 14
	v_lshl_add_u64 v[0:1], v[214:215], 0, s[12:13]
	v_lshl_add_u64 v[4:5], v[216:217], 0, s[12:13]
	global_load_dwordx4 v[156:159], v[0:1], off
	global_load_dwordx4 v[160:163], v[4:5], off

.LBB0_898:
	v_exp_f32_e32 v112, v80
	v_exp_f32_e32 v80, v96
	v_exp_f32_e32 v113, v81
	v_exp_f32_e32 v81, v97
	v_exp_f32_e32 v114, v82
	v_exp_f32_e32 v82, v98
	v_exp_f32_e32 v115, v83
	v_exp_f32_e32 v83, v99
	v_exp_f32_e32 v116, v84
	v_exp_f32_e32 v84, v100
	v_exp_f32_e32 v117, v85
	v_exp_f32_e32 v85, v101
	v_exp_f32_e32 v118, v86
	v_exp_f32_e32 v86, v102
	v_exp_f32_e32 v119, v87
	v_exp_f32_e32 v87, v103
	v_exp_f32_e32 v120, v88
	v_exp_f32_e32 v88, v104
	v_exp_f32_e32 v121, v89
	v_exp_f32_e32 v89, v105
	v_exp_f32_e32 v122, v90
	v_exp_f32_e32 v90, v106
	v_exp_f32_e32 v123, v91
	v_exp_f32_e32 v91, v107
	v_exp_f32_e32 v124, v92
	v_exp_f32_e32 v92, v108
	v_exp_f32_e32 v125, v93
	v_exp_f32_e32 v93, v109
	v_exp_f32_e32 v126, v94
	v_exp_f32_e32 v94, v110
	v_exp_f32_e32 v127, v95
	v_exp_f32_e32 v95, v111
	v_add_f32_e32 v0, v112, v80
	v_add_f32_e32 v1, v113, v81
	v_add_f32_e32 v96, v115, v83
	v_add_f32_e32 v3, v114, v82
	v_cvt_pk_bf16_f32 v97, v114, v115
	v_add_f32_e32 v0, v0, v116
	v_add_f32_e32 v1, v1, v117
	v_add_f32_e32 v96, v96, v119
	v_add_f32_e32 v3, v3, v118
	v_cvt_pk_bf16_f32 v98, v116, v117
	v_add_f32_e32 v0, v0, v84
	v_add_f32_e32 v1, v1, v85
	v_add_f32_e32 v96, v96, v87
	v_add_f32_e32 v3, v3, v86
	v_cvt_pk_bf16_f32 v99, v118, v119
	v_add_f32_e32 v0, v0, v120
	v_add_f32_e32 v1, v1, v121
	v_add_f32_e32 v96, v96, v123
	v_add_f32_e32 v3, v3, v122
	v_cvt_pk_bf16_f32 v100, v120, v121
	v_add_f32_e32 v0, v0, v88
	v_add_f32_e32 v1, v1, v89
	v_add_f32_e32 v96, v96, v91
	v_add_f32_e32 v3, v3, v90
	v_cvt_pk_bf16_f32 v101, v122, v123
	v_add_f32_e32 v0, v0, v124
	v_add_f32_e32 v1, v1, v125
	v_add_f32_e32 v96, v96, v127
	v_add_f32_e32 v3, v3, v126
	v_cvt_pk_bf16_f32 v102, v124, v125
	v_add_f32_e32 v0, v0, v92
	v_add_f32_e32 v1, v1, v93
	v_add_f32_e32 v96, v96, v95
	v_add_f32_e32 v3, v3, v94
	v_cvt_pk_bf16_f32 v103, v126, v127
	v_add_f32_e32 v0, v0, v1
	v_add_f32_e32 v1, v3, v96
	v_cvt_pk_bf16_f32 v96, v112, v113
	v_add_f32_e32 v0, v0, v1
	v_cvt_pk_bf16_f32 v80, v80, v81
	v_cvt_pk_bf16_f32 v81, v82, v83
	v_cvt_pk_bf16_f32 v82, v84, v85
	v_cvt_pk_bf16_f32 v83, v86, v87
	v_cvt_pk_bf16_f32 v84, v88, v89
	v_cvt_pk_bf16_f32 v85, v90, v91
	v_cvt_pk_bf16_f32 v86, v92, v93
	v_cvt_pk_bf16_f32 v87, v94, v95
	s_waitcnt vmcnt(1)
	ds_write_b128 v192, v[148:151]
	s_waitcnt vmcnt(0)
	ds_write_b128 v194, v[152:155] offset:18432
	s_setprio 1
	v_mfma_f32_32x32x16_bf16 v[32:47], v[4:7], v[96:99], v[32:47]
	s_waitcnt lgkmcnt(12)
	v_mfma_f32_32x32x16_bf16 v[16:31], v[8:11], v[96:99], v[16:31]
	s_waitcnt lgkmcnt(10)
	v_mfma_f32_32x32x16_bf16 v[32:47], v[12:15], v[100:103], v[32:47]
	s_waitcnt lgkmcnt(8)
	v_mfma_f32_32x32x16_bf16 v[16:31], v[164:167], v[100:103], v[16:31]
	s_waitcnt lgkmcnt(6)
	v_mfma_f32_32x32x16_bf16 v[32:47], v[168:171], v[80:83], v[32:47]
	s_waitcnt lgkmcnt(4)
	v_mfma_f32_32x32x16_bf16 v[16:31], v[172:175], v[80:83], v[16:31]
	s_waitcnt lgkmcnt(2)
	v_mfma_f32_32x32x16_bf16 v[32:47], v[176:179], v[84:87], v[32:47]
	s_waitcnt lgkmcnt(0)
	v_mfma_f32_32x32x16_bf16 v[16:31], v[180:183], v[84:87], v[16:31]
	s_setprio 0
	s_andn2_b64 vcc, exec, s[54:55]
	s_mov_b64 s[16:17], -1
	s_cbranch_vccnz .LBB0_871
	s_lshl_b64 s[12:13], 1, s2
	s_andn2_b64 s[12:13], s[58:59], s[12:13]
	s_mov_b64 s[16:17], 0
	s_waitcnt lgkmcnt(0)
	s_barrier
	s_branch .LBB0_871

.LBB0_951:
	ds_read_b128 v[4:7], v239
	ds_read_b128 v[8:11], v239 offset:32
	ds_read_b128 v[12:15], v239 offset:4608
	ds_read_b128 v[96:99], v239 offset:4640
	ds_read_b128 v[100:103], v239 offset:64
	ds_read_b128 v[104:107], v239 offset:96
	ds_read_b128 v[108:111], v239 offset:4672
	ds_read_b128 v[112:115], v239 offset:4704
	s_cmp_lg_u64 s[24:25], 0
	s_cselect_b64 s[22:23], -1, 0
	s_ff1_i32_b64 s0, s[24:25]
	s_and_b64 s[12:13], s[22:23], exec
	s_cselect_b32 s12, s0, -1
	s_cmp_lt_i32 s12, 0
	s_cbranch_scc1 .LBB0_953
	v_mad_u64_u32 v[0:1], s[12:13], s12, v243, v[224:225]
	global_load_dwordx4 v[148:151], v[0:1], off offset:1536
	global_load_dwordx4 v[152:155], v[0:1], off offset:1792
.LBB0_953:
	v_lshrrev_b64 v[0:1], s2, v[214:215]
	v_and_b32_e32 v0, 1, v0
	s_lshl_b32 s26, s2, 6
	v_cmp_eq_u32_e64 s[16:17], 1, v0
	s_setprio 1
	s_waitcnt lgkmcnt(7)
	v_mfma_f32_32x32x16_bf16 v[64:79], v[4:7], v[132:135], v[48:63]
	s_waitcnt lgkmcnt(5)
	v_mfma_f32_32x32x16_bf16 v[80:95], v[12:15], v[132:135], v[48:63]
	s_setprio 0
	v_mfma_f32_32x32x16_bf16 v[64:79], v[8:11], v[136:139], v[64:79]
	ds_read_b64_tr_b16 v[4:5], v235 offset:18432
	ds_read_b64_tr_b16 v[6:7], v235 offset:19968
	ds_read_b64_tr_b16 v[10:11], v235 offset:20032
	ds_read_b64_tr_b16 v[8:9], v235 offset:18496
	ds_read_b64_tr_b16 v[12:13], v235 offset:21504
	ds_read_b64_tr_b16 v[14:15], v235 offset:23040
	ds_read_b64_tr_b16 v[166:167], v235 offset:23104
	ds_read_b64_tr_b16 v[164:165], v235 offset:21568
	ds_read_b64_tr_b16 v[168:169], v235 offset:24576
	ds_read_b64_tr_b16 v[170:171], v235 offset:26112
	ds_read_b64_tr_b16 v[174:175], v235 offset:26176
	ds_read_b64_tr_b16 v[172:173], v235 offset:24640
	ds_read_b64_tr_b16 v[176:177], v235 offset:27648
	ds_read_b64_tr_b16 v[178:179], v235 offset:29184
	ds_read_b64_tr_b16 v[182:183], v235 offset:29248
	ds_read_b64_tr_b16 v[180:181], v235 offset:27712
	s_waitcnt lgkmcnt(14)
	v_mfma_f32_32x32x16_bf16 v[80:95], v[96:99], v[136:139], v[80:95]
	v_mfma_f32_32x32x16_bf16 v[64:79], v[100:103], v[140:143], v[64:79]
	v_mfma_f32_32x32x16_bf16 v[80:95], v[108:111], v[140:143], v[80:95]
	v_mfma_f32_32x32x16_bf16 v[64:79], v[104:107], v[144:147], v[64:79]
	v_mfma_f32_32x32x16_bf16 v[80:95], v[112:115], v[144:147], v[80:95]
	s_or_b32 s2, s26, 63
	v_cmp_le_u32_e32 vcc, s2, v246
	s_cmp_eq_u64 vcc, exec
	s_cbranch_scc1 .LBB0_956
	v_or_b32_e32 v0, s26, v237
	v_cmp_le_u32_e32 vcc, v0, v246
	s_and_b64 vcc, s[16:17], vcc
	v_or_b32_e32 v1, 32, v0
	s_nop 2
	v_cndmask_b32_e32 v96, v244, v64, vcc
	v_cmp_le_u32_e32 vcc, v1, v246
	s_and_b64 vcc, s[16:17], vcc
	v_or_b32_e32 v1, 33, v0
	v_cndmask_b32_e32 v112, v244, v80, vcc
	v_cmp_lt_u32_e32 vcc, v0, v246
	s_and_b64 vcc, s[16:17], vcc
	s_xor_b64 s[12:13], s[16:17], -1
	v_cndmask_b32_e32 v97, v244, v65, vcc
	v_cmp_le_u32_e32 vcc, v1, v246
	s_and_b64 vcc, s[16:17], vcc
	v_or_b32_e32 v1, 2, v0
	v_cndmask_b32_e32 v113, v244, v81, vcc
	v_cmp_le_u32_e32 vcc, v1, v246
	s_and_b64 vcc, s[16:17], vcc
	v_or_b32_e32 v1, 34, v0
	v_cndmask_b32_e32 v98, v244, v66, vcc
	v_cmp_le_u32_e32 vcc, v1, v246
	v_or_b32_e32 v1, s26, v236
	s_and_b64 vcc, s[16:17], vcc
	v_or_b32_e32 v3, 3, v1
	v_cndmask_b32_e32 v114, v244, v82, vcc
	v_cmp_le_u32_e32 vcc, v3, v246
	s_and_b64 vcc, s[16:17], vcc
	v_or_b32_e32 v3, 35, v1
	v_cndmask_b32_e32 v99, v244, v67, vcc
	v_cmp_le_u32_e32 vcc, v3, v246
	s_and_b64 vcc, s[16:17], vcc
	v_or_b32_e32 v3, 8, v0
	v_cndmask_b32_e32 v115, v244, v83, vcc
	v_cmp_le_u32_e32 vcc, v3, v246
	s_and_b64 vcc, s[16:17], vcc
	v_or_b32_e32 v3, 40, v0
	v_cndmask_b32_e32 v100, v244, v68, vcc
	v_cmp_le_u32_e32 vcc, v3, v246
	s_and_b64 vcc, s[16:17], vcc
	v_or_b32_e32 v3, 9, v0
	v_cndmask_b32_e32 v116, v244, v84, vcc
	v_cmp_le_u32_e32 vcc, v3, v246
	s_and_b64 vcc, s[16:17], vcc
	v_or_b32_e32 v3, 41, v0
	v_cndmask_b32_e32 v101, v244, v69, vcc
	v_cmp_le_u32_e32 vcc, v3, v246
	s_and_b64 vcc, s[16:17], vcc
	v_or_b32_e32 v3, 10, v0
	v_cndmask_b32_e32 v117, v244, v85, vcc
	v_cmp_le_u32_e32 vcc, v3, v246
	s_and_b64 vcc, s[16:17], vcc
	v_or_b32_e32 v3, 42, v0
	v_cndmask_b32_e32 v102, v244, v70, vcc
	v_cmp_le_u32_e32 vcc, v3, v246
	s_and_b64 vcc, s[16:17], vcc
	v_or_b32_e32 v3, 11, v1
	v_cndmask_b32_e32 v118, v244, v86, vcc
	v_cmp_le_u32_e32 vcc, v3, v246
	s_and_b64 vcc, s[16:17], vcc
	v_or_b32_e32 v3, 43, v1
	v_cndmask_b32_e32 v103, v244, v71, vcc
	v_cmp_le_u32_e32 vcc, v3, v246
	s_and_b64 vcc, s[16:17], vcc
	v_or_b32_e32 v3, 16, v0
	v_cndmask_b32_e32 v119, v244, v87, vcc
	v_cmp_le_u32_e32 vcc, v3, v246
	s_and_b64 vcc, s[16:17], vcc
	v_or_b32_e32 v3, 48, v0
	v_cndmask_b32_e32 v104, v244, v72, vcc
	v_cmp_le_u32_e32 vcc, v3, v246
	s_and_b64 vcc, s[16:17], vcc
	v_or_b32_e32 v3, 17, v0
	v_cndmask_b32_e32 v120, v244, v88, vcc
	v_cmp_le_u32_e32 vcc, v3, v246
	s_and_b64 vcc, s[16:17], vcc
	v_or_b32_e32 v3, 49, v0
	v_cndmask_b32_e32 v105, v244, v73, vcc
	v_cmp_le_u32_e32 vcc, v3, v246
	s_and_b64 vcc, s[16:17], vcc
	v_or_b32_e32 v3, 18, v0
	v_cndmask_b32_e32 v121, v244, v89, vcc
	v_cmp_le_u32_e32 vcc, v3, v246
	s_and_b64 vcc, s[16:17], vcc
	v_or_b32_e32 v3, 50, v0
	v_cndmask_b32_e32 v106, v244, v74, vcc
	v_cmp_le_u32_e32 vcc, v3, v246
	s_and_b64 vcc, s[16:17], vcc
	v_or_b32_e32 v3, 19, v1
	v_cndmask_b32_e32 v122, v244, v90, vcc
	v_cmp_le_u32_e32 vcc, v3, v246
	s_and_b64 vcc, s[16:17], vcc
	v_or_b32_e32 v3, 51, v1
	v_cndmask_b32_e32 v107, v244, v75, vcc
	v_cmp_le_u32_e32 vcc, v3, v246
	s_and_b64 vcc, s[16:17], vcc
	v_or_b32_e32 v3, 24, v0
	v_cndmask_b32_e32 v123, v244, v91, vcc
	v_cmp_le_u32_e32 vcc, v3, v246
	s_and_b64 vcc, s[16:17], vcc
	v_or_b32_e32 v3, 56, v0
	v_cndmask_b32_e32 v108, v244, v76, vcc
	v_cmp_le_u32_e32 vcc, v3, v246
	s_and_b64 vcc, s[16:17], vcc
	v_or_b32_e32 v3, 25, v0
	v_cndmask_b32_e32 v124, v244, v92, vcc
	v_cmp_le_u32_e32 vcc, v3, v246
	s_and_b64 vcc, s[16:17], vcc
	v_or_b32_e32 v3, 57, v0
	v_cndmask_b32_e32 v109, v244, v77, vcc
	v_cmp_le_u32_e32 vcc, v3, v246
	s_and_b64 vcc, s[16:17], vcc
	v_or_b32_e32 v3, 26, v0
	v_cndmask_b32_e32 v125, v244, v93, vcc
	v_cmp_le_u32_e32 vcc, v3, v246
	s_and_b64 vcc, s[16:17], vcc
	v_or_b32_e32 v0, 58, v0
	v_cndmask_b32_e32 v110, v244, v78, vcc
	v_cmp_le_u32_e32 vcc, v0, v246
	s_and_b64 vcc, s[16:17], vcc
	v_or_b32_e32 v0, 27, v1
	v_cndmask_b32_e32 v126, v244, v94, vcc
	v_cmp_le_u32_e32 vcc, v0, v246
	s_and_b64 vcc, s[16:17], vcc
	v_or_b32_e32 v0, 59, v1
	v_cndmask_b32_e32 v111, v244, v79, vcc
	v_cmp_gt_u32_e32 vcc, v0, v246
	s_or_b64 s[12:13], s[12:13], vcc
	v_mov_b32_e32 v127, v95
	s_and_b64 s[12:13], s[12:13], exec
	v_mov_b32_e32 v0, 0xff800000
	s_cbranch_execz .LBB0_957
	v_mov_b64_e32 v[80:81], v[112:113]
	v_mov_b64_e32 v[82:83], v[114:115]
	v_mov_b64_e32 v[84:85], v[116:117]
	v_mov_b64_e32 v[86:87], v[118:119]
	v_mov_b64_e32 v[88:89], v[120:121]
	v_mov_b64_e32 v[90:91], v[122:123]
	v_mov_b64_e32 v[92:93], v[124:125]
	v_mov_b64_e32 v[94:95], v[126:127]
	s_and_saveexec_b64 s[16:17], s[12:13]
	s_cbranch_execnz .LBB0_961
	s_branch .LBB0_962

.LBB0_969:
	v_exp_f32_e32 v96, v96
	v_exp_f32_e32 v80, v80
	v_exp_f32_e32 v97, v97
	v_exp_f32_e32 v81, v81
	v_exp_f32_e32 v98, v98
	v_exp_f32_e32 v82, v82
	v_exp_f32_e32 v99, v99
	v_exp_f32_e32 v83, v83
	v_exp_f32_e32 v100, v100
	v_exp_f32_e32 v84, v84
	v_exp_f32_e32 v101, v101
	v_exp_f32_e32 v85, v85
	v_exp_f32_e32 v102, v102
	v_exp_f32_e32 v86, v86
	v_exp_f32_e32 v103, v103
	v_exp_f32_e32 v87, v87
	v_exp_f32_e32 v104, v104
	v_exp_f32_e32 v88, v88
	v_exp_f32_e32 v105, v105
	v_exp_f32_e32 v89, v89
	v_exp_f32_e32 v106, v106
	v_exp_f32_e32 v90, v90
	v_exp_f32_e32 v107, v107
	v_exp_f32_e32 v91, v91
	v_exp_f32_e32 v108, v108
	v_exp_f32_e32 v92, v92
	v_exp_f32_e32 v109, v109
	v_exp_f32_e32 v93, v93
	v_exp_f32_e32 v110, v110
	v_exp_f32_e32 v94, v94
	v_exp_f32_e32 v111, v111
	v_exp_f32_e32 v95, v95
	s_mov_b64 s[16:17], -1
	v_add_f32_e32 v0, v96, v80
	v_add_f32_e32 v1, v97, v81
	v_add_f32_e32 v3, v98, v82
	v_add_f32_e32 v112, v99, v83
	v_cvt_pk_bf16_f32 v96, v96, v97
	v_add_f32_e32 v0, v0, v100
	v_add_f32_e32 v1, v1, v101
	v_add_f32_e32 v3, v3, v102
	v_add_f32_e32 v112, v112, v103
	v_cvt_pk_bf16_f32 v97, v98, v99
	v_add_f32_e32 v0, v0, v84
	v_add_f32_e32 v1, v1, v85
	v_add_f32_e32 v3, v3, v86
	v_add_f32_e32 v112, v112, v87
	v_cvt_pk_bf16_f32 v98, v100, v101
	v_add_f32_e32 v0, v0, v104
	v_add_f32_e32 v1, v1, v105
	v_add_f32_e32 v3, v3, v106
	v_add_f32_e32 v112, v112, v107
	v_cvt_pk_bf16_f32 v99, v102, v103
	v_add_f32_e32 v0, v0, v88
	v_add_f32_e32 v1, v1, v89
	v_add_f32_e32 v3, v3, v90
	v_add_f32_e32 v112, v112, v91
	v_cvt_pk_bf16_f32 v100, v104, v105
	v_add_f32_e32 v0, v0, v108
	v_add_f32_e32 v1, v1, v109
	v_add_f32_e32 v3, v3, v110
	v_add_f32_e32 v112, v112, v111
	v_cvt_pk_bf16_f32 v101, v106, v107
	v_add_f32_e32 v0, v0, v92
	v_add_f32_e32 v1, v1, v93
	v_add_f32_e32 v3, v3, v94
	v_add_f32_e32 v112, v112, v95
	v_cvt_pk_bf16_f32 v102, v108, v109
	v_add_f32_e32 v0, v0, v1
	v_add_f32_e32 v1, v3, v112
	v_cvt_pk_bf16_f32 v103, v110, v111
	v_add_f32_e32 v0, v0, v1
	v_cvt_pk_bf16_f32 v80, v80, v81
	v_add_f32_e32 v226, v226, v0
	v_cvt_pk_bf16_f32 v81, v82, v83
	v_cvt_pk_bf16_f32 v82, v84, v85
	v_cvt_pk_bf16_f32 v83, v86, v87
	v_cvt_pk_bf16_f32 v84, v88, v89
	v_cvt_pk_bf16_f32 v85, v90, v91
	v_cvt_pk_bf16_f32 v86, v92, v93
	v_cvt_pk_bf16_f32 v87, v94, v95
	s_waitcnt vmcnt(1)
	ds_write_b128 v192, v[156:159] offset:9216
	s_waitcnt vmcnt(0)
	ds_write_b128 v194, v[160:163] offset:30720
	s_setprio 1
	v_mfma_f32_32x32x16_bf16 v[32:47], v[4:7], v[96:99], v[32:47]
	s_waitcnt lgkmcnt(12)
	v_mfma_f32_32x32x16_bf16 v[16:31], v[8:11], v[96:99], v[16:31]
	s_waitcnt lgkmcnt(10)
	v_mfma_f32_32x32x16_bf16 v[32:47], v[12:15], v[100:103], v[32:47]
	s_waitcnt lgkmcnt(8)
	v_mfma_f32_32x32x16_bf16 v[16:31], v[164:167], v[100:103], v[16:31]
	s_waitcnt lgkmcnt(6)
	v_mfma_f32_32x32x16_bf16 v[32:47], v[168:171], v[80:83], v[32:47]
	s_waitcnt lgkmcnt(4)
	v_mfma_f32_32x32x16_bf16 v[16:31], v[172:175], v[80:83], v[16:31]
	s_waitcnt lgkmcnt(2)
	v_mfma_f32_32x32x16_bf16 v[32:47], v[176:179], v[84:87], v[32:47]
	s_waitcnt lgkmcnt(0)
	v_mfma_f32_32x32x16_bf16 v[16:31], v[180:183], v[84:87], v[16:31]
	s_setprio 0
	s_cmp_lt_i32 s28, 0
	s_cbranch_scc1 .LBB0_975
	s_lshl_b64 s[12:13], 1, s0
	s_andn2_b64 s[12:13], s[24:25], s[12:13]
	s_ff1_i32_b64 s30, s[12:13]
	s_cmp_lg_u64 s[12:13], 0
	s_cselect_b32 s29, s30, -1
	s_cmp_lt_i32 s29, 0
	s_waitcnt lgkmcnt(0)
	s_barrier
	ds_read_b128 v[4:7], v239 offset:9216
	ds_read_b128 v[8:11], v239 offset:9248
	ds_read_b128 v[12:15], v239 offset:13824
	ds_read_b128 v[80:83], v239 offset:13856
	ds_read_b128 v[84:87], v239 offset:9280
	ds_read_b128 v[88:91], v239 offset:9312
	ds_read_b128 v[92:95], v239 offset:13888
	ds_read_b128 v[112:115], v239 offset:13920
	s_cbranch_scc1 .LBB0_972
	v_mad_u64_u32 v[0:1], s[16:17], s29, v243, v[224:225]
	global_load_dwordx4 v[156:159], v[0:1], off offset:1536
	global_load_dwordx4 v[160:163], v[0:1], off offset:1792
.LBB0_972:
	v_lshrrev_b64 v[0:1], s28, v[214:215]
	v_and_b32_e32 v0, 1, v0
	s_lshl_b32 s2, s28, 6
	v_cmp_eq_u32_e64 s[16:17], 1, v0
	s_setprio 1
	s_waitcnt lgkmcnt(7)
	v_mfma_f32_32x32x16_bf16 v[96:111], v[4:7], v[132:135], v[64:79]
	s_waitcnt lgkmcnt(5)
	v_mfma_f32_32x32x16_bf16 v[64:79], v[12:15], v[132:135], v[64:79]
	s_setprio 0
	v_mfma_f32_32x32x16_bf16 v[96:111], v[8:11], v[136:139], v[96:111]
	ds_read_b64_tr_b16 v[4:5], v235 offset:30720
	ds_read_b64_tr_b16 v[6:7], v235 offset:32256
	ds_read_b64_tr_b16 v[10:11], v235 offset:32320
	ds_read_b64_tr_b16 v[8:9], v235 offset:30784
	ds_read_b64_tr_b16 v[12:13], v235 offset:33792
	ds_read_b64_tr_b16 v[14:15], v235 offset:35328
	ds_read_b64_tr_b16 v[166:167], v235 offset:35392
	ds_read_b64_tr_b16 v[164:165], v235 offset:33856
	ds_read_b64_tr_b16 v[168:169], v235 offset:36864
	ds_read_b64_tr_b16 v[170:171], v235 offset:38400
	ds_read_b64_tr_b16 v[174:175], v235 offset:38464
	ds_read_b64_tr_b16 v[172:173], v235 offset:36928
	ds_read_b64_tr_b16 v[176:177], v235 offset:39936
	ds_read_b64_tr_b16 v[178:179], v235 offset:41472
	ds_read_b64_tr_b16 v[182:183], v235 offset:41536
	ds_read_b64_tr_b16 v[180:181], v235 offset:40000
	s_waitcnt lgkmcnt(14)
	v_mfma_f32_32x32x16_bf16 v[64:79], v[80:83], v[136:139], v[64:79]
	v_mfma_f32_32x32x16_bf16 v[96:111], v[84:87], v[140:143], v[96:111]
	v_mfma_f32_32x32x16_bf16 v[64:79], v[92:95], v[140:143], v[64:79]
	v_mfma_f32_32x32x16_bf16 v[96:111], v[88:91], v[144:147], v[96:111]
	v_mfma_f32_32x32x16_bf16 v[64:79], v[112:115], v[144:147], v[64:79]
	s_or_b32 s24, s2, 63
	v_cmp_le_u32_e32 vcc, s24, v246
	s_cmp_eq_u64 vcc, exec
	s_cbranch_scc1 .LBB0_976
	v_or_b32_e32 v0, s2, v237
	v_cmp_le_u32_e32 vcc, v0, v246
	s_and_b64 vcc, s[16:17], vcc
	v_or_b32_e32 v1, 32, v0
	s_nop 2
	v_cndmask_b32_e32 v80, v244, v96, vcc
	v_cmp_le_u32_e32 vcc, v1, v246
	s_and_b64 vcc, s[16:17], vcc
	v_or_b32_e32 v1, 33, v0
	v_cndmask_b32_e32 v112, v244, v64, vcc
	v_cmp_lt_u32_e32 vcc, v0, v246
	s_and_b64 vcc, s[16:17], vcc
	s_xor_b64 s[24:25], s[16:17], -1
	v_cndmask_b32_e32 v81, v244, v97, vcc
	v_cmp_le_u32_e32 vcc, v1, v246
	s_and_b64 vcc, s[16:17], vcc
	v_or_b32_e32 v1, 2, v0
	v_cndmask_b32_e32 v113, v244, v65, vcc
	v_cmp_le_u32_e32 vcc, v1, v246
	s_and_b64 vcc, s[16:17], vcc
	v_or_b32_e32 v1, 34, v0
	v_cndmask_b32_e32 v82, v244, v98, vcc
	v_cmp_le_u32_e32 vcc, v1, v246
	v_or_b32_e32 v1, s2, v236
	s_and_b64 vcc, s[16:17], vcc
	v_or_b32_e32 v3, 3, v1
	v_cndmask_b32_e32 v114, v244, v66, vcc
	v_cmp_le_u32_e32 vcc, v3, v246
	s_and_b64 vcc, s[16:17], vcc
	v_or_b32_e32 v3, 35, v1
	v_cndmask_b32_e32 v83, v244, v99, vcc
	v_cmp_le_u32_e32 vcc, v3, v246
	s_and_b64 vcc, s[16:17], vcc
	v_or_b32_e32 v3, 8, v0
	v_cndmask_b32_e32 v115, v244, v67, vcc
	v_cmp_le_u32_e32 vcc, v3, v246
	s_and_b64 vcc, s[16:17], vcc
	v_or_b32_e32 v3, 40, v0
	v_cndmask_b32_e32 v84, v244, v100, vcc
	v_cmp_le_u32_e32 vcc, v3, v246
	s_and_b64 vcc, s[16:17], vcc
	v_or_b32_e32 v3, 9, v0
	v_cndmask_b32_e32 v116, v244, v68, vcc
	v_cmp_le_u32_e32 vcc, v3, v246
	s_and_b64 vcc, s[16:17], vcc
	v_or_b32_e32 v3, 41, v0
	v_cndmask_b32_e32 v85, v244, v101, vcc
	v_cmp_le_u32_e32 vcc, v3, v246
	s_and_b64 vcc, s[16:17], vcc
	v_or_b32_e32 v3, 10, v0
	v_cndmask_b32_e32 v117, v244, v69, vcc
	v_cmp_le_u32_e32 vcc, v3, v246
	s_and_b64 vcc, s[16:17], vcc
	v_or_b32_e32 v3, 42, v0
	v_cndmask_b32_e32 v86, v244, v102, vcc
	v_cmp_le_u32_e32 vcc, v3, v246
	s_and_b64 vcc, s[16:17], vcc
	v_or_b32_e32 v3, 11, v1
	v_cndmask_b32_e32 v118, v244, v70, vcc
	v_cmp_le_u32_e32 vcc, v3, v246
	s_and_b64 vcc, s[16:17], vcc
	v_or_b32_e32 v3, 43, v1
	v_cndmask_b32_e32 v87, v244, v103, vcc
	v_cmp_le_u32_e32 vcc, v3, v246
	s_and_b64 vcc, s[16:17], vcc
	v_or_b32_e32 v3, 16, v0
	v_cndmask_b32_e32 v119, v244, v71, vcc
	v_cmp_le_u32_e32 vcc, v3, v246
	s_and_b64 vcc, s[16:17], vcc
	v_or_b32_e32 v3, 48, v0
	v_cndmask_b32_e32 v88, v244, v104, vcc
	v_cmp_le_u32_e32 vcc, v3, v246
	s_and_b64 vcc, s[16:17], vcc
	v_or_b32_e32 v3, 17, v0
	v_cndmask_b32_e32 v120, v244, v72, vcc
	v_cmp_le_u32_e32 vcc, v3, v246
	s_and_b64 vcc, s[16:17], vcc
	v_or_b32_e32 v3, 49, v0
	v_cndmask_b32_e32 v89, v244, v105, vcc
	v_cmp_le_u32_e32 vcc, v3, v246
	s_and_b64 vcc, s[16:17], vcc
	v_or_b32_e32 v3, 18, v0
	v_cndmask_b32_e32 v121, v244, v73, vcc
	v_cmp_le_u32_e32 vcc, v3, v246
	s_and_b64 vcc, s[16:17], vcc
	v_or_b32_e32 v3, 50, v0
	v_cndmask_b32_e32 v90, v244, v106, vcc
	v_cmp_le_u32_e32 vcc, v3, v246
	s_and_b64 vcc, s[16:17], vcc
	v_or_b32_e32 v3, 19, v1
	v_cndmask_b32_e32 v122, v244, v74, vcc
	v_cmp_le_u32_e32 vcc, v3, v246
	s_and_b64 vcc, s[16:17], vcc
	v_or_b32_e32 v3, 51, v1
	v_cndmask_b32_e32 v91, v244, v107, vcc
	v_cmp_le_u32_e32 vcc, v3, v246
	s_and_b64 vcc, s[16:17], vcc
	v_or_b32_e32 v3, 24, v0
	v_cndmask_b32_e32 v123, v244, v75, vcc
	v_cmp_le_u32_e32 vcc, v3, v246
	s_and_b64 vcc, s[16:17], vcc
	v_or_b32_e32 v3, 56, v0
	v_cndmask_b32_e32 v92, v244, v108, vcc
	v_cmp_le_u32_e32 vcc, v3, v246
	s_and_b64 vcc, s[16:17], vcc
	v_or_b32_e32 v3, 25, v0
	v_cndmask_b32_e32 v124, v244, v76, vcc
	v_cmp_le_u32_e32 vcc, v3, v246
	s_and_b64 vcc, s[16:17], vcc
	v_or_b32_e32 v3, 57, v0
	v_cndmask_b32_e32 v93, v244, v109, vcc
	v_cmp_le_u32_e32 vcc, v3, v246
	s_and_b64 vcc, s[16:17], vcc
	v_or_b32_e32 v3, 26, v0
	v_cndmask_b32_e32 v125, v244, v77, vcc
	v_cmp_le_u32_e32 vcc, v3, v246
	s_and_b64 vcc, s[16:17], vcc
	v_or_b32_e32 v0, 58, v0
	v_cndmask_b32_e32 v94, v244, v110, vcc
	v_cmp_le_u32_e32 vcc, v0, v246
	s_and_b64 vcc, s[16:17], vcc
	v_or_b32_e32 v0, 27, v1
	v_cndmask_b32_e32 v126, v244, v78, vcc
	v_cmp_le_u32_e32 vcc, v0, v246
	s_and_b64 vcc, s[16:17], vcc
	v_or_b32_e32 v0, 59, v1
	v_cndmask_b32_e32 v95, v244, v111, vcc
	v_cmp_gt_u32_e32 vcc, v0, v246
	s_or_b64 s[24:25], s[24:25], vcc
	v_mov_b32_e32 v127, v79
	s_and_b64 s[24:25], s[24:25], exec
	v_mov_b32_e32 v0, 0xff800000
	s_cbranch_execz .LBB0_977
	v_mov_b64_e32 v[64:65], v[112:113]
	v_mov_b64_e32 v[66:67], v[114:115]
	v_mov_b64_e32 v[68:69], v[116:117]
	v_mov_b64_e32 v[70:71], v[118:119]
	v_mov_b64_e32 v[72:73], v[120:121]
	v_mov_b64_e32 v[74:75], v[122:123]
	v_mov_b64_e32 v[76:77], v[124:125]
	v_mov_b64_e32 v[78:79], v[126:127]
	s_and_saveexec_b64 s[16:17], s[24:25]
	s_cbranch_execnz .LBB0_981
	s_branch .LBB0_982

.LBB0_988:
	v_exp_f32_e32 v80, v80
	v_exp_f32_e32 v64, v64
	v_exp_f32_e32 v81, v81
	v_exp_f32_e32 v65, v65
	v_exp_f32_e32 v82, v82
	v_exp_f32_e32 v66, v66
	v_exp_f32_e32 v83, v83
	v_exp_f32_e32 v67, v67
	v_exp_f32_e32 v84, v84
	v_exp_f32_e32 v68, v68
	v_exp_f32_e32 v85, v85
	v_exp_f32_e32 v69, v69
	v_exp_f32_e32 v86, v86
	v_exp_f32_e32 v70, v70
	v_exp_f32_e32 v87, v87
	v_exp_f32_e32 v71, v71
	v_exp_f32_e32 v88, v88
	v_exp_f32_e32 v72, v72
	v_exp_f32_e32 v89, v89
	v_exp_f32_e32 v73, v73
	v_exp_f32_e32 v90, v90
	v_exp_f32_e32 v74, v74
	v_exp_f32_e32 v91, v91
	v_exp_f32_e32 v75, v75
	v_exp_f32_e32 v92, v92
	v_exp_f32_e32 v76, v76
	v_exp_f32_e32 v93, v93
	v_exp_f32_e32 v77, v77
	v_exp_f32_e32 v94, v94
	v_exp_f32_e32 v78, v78
	v_exp_f32_e32 v95, v95
	v_exp_f32_e32 v79, v79
	v_add_f32_e32 v0, v80, v64
	v_add_f32_e32 v1, v81, v65
	v_add_f32_e32 v3, v82, v66
	v_add_f32_e32 v96, v83, v67
	v_cvt_pk_bf16_f32 v80, v80, v81
	v_add_f32_e32 v0, v0, v84
	v_add_f32_e32 v1, v1, v85
	v_add_f32_e32 v3, v3, v86
	v_add_f32_e32 v96, v96, v87
	v_cvt_pk_bf16_f32 v81, v82, v83
	v_add_f32_e32 v0, v0, v68
	v_add_f32_e32 v1, v1, v69
	v_add_f32_e32 v3, v3, v70
	v_add_f32_e32 v96, v96, v71
	v_cvt_pk_bf16_f32 v82, v84, v85
	v_add_f32_e32 v0, v0, v88
	v_add_f32_e32 v1, v1, v89
	v_add_f32_e32 v3, v3, v90
	v_add_f32_e32 v96, v96, v91
	v_cvt_pk_bf16_f32 v83, v86, v87
	v_add_f32_e32 v0, v0, v72
	v_add_f32_e32 v1, v1, v73
	v_add_f32_e32 v3, v3, v74
	v_add_f32_e32 v96, v96, v75
	v_cvt_pk_bf16_f32 v84, v88, v89
	v_add_f32_e32 v0, v0, v92
	v_add_f32_e32 v1, v1, v93
	v_add_f32_e32 v3, v3, v94
	v_add_f32_e32 v96, v96, v95
	v_cvt_pk_bf16_f32 v85, v90, v91
	v_add_f32_e32 v0, v0, v76
	v_add_f32_e32 v1, v1, v77
	v_add_f32_e32 v3, v3, v78
	v_add_f32_e32 v96, v96, v79
	v_cvt_pk_bf16_f32 v86, v92, v93
	v_add_f32_e32 v0, v0, v1
	v_add_f32_e32 v1, v3, v96
	v_cvt_pk_bf16_f32 v87, v94, v95
	v_add_f32_e32 v0, v0, v1
	v_cvt_pk_bf16_f32 v64, v64, v65
	v_cvt_pk_bf16_f32 v65, v66, v67
	v_cvt_pk_bf16_f32 v66, v68, v69
	v_cvt_pk_bf16_f32 v67, v70, v71
	v_cvt_pk_bf16_f32 v68, v72, v73
	v_cvt_pk_bf16_f32 v69, v74, v75
	v_cvt_pk_bf16_f32 v70, v76, v77
	v_cvt_pk_bf16_f32 v71, v78, v79
	s_waitcnt vmcnt(1)
	ds_write_b128 v192, v[148:151]
	s_waitcnt vmcnt(0)
	ds_write_b128 v194, v[152:155] offset:18432
	s_setprio 1
	v_mfma_f32_32x32x16_bf16 v[32:47], v[4:7], v[80:83], v[32:47]
	s_waitcnt lgkmcnt(12)
	v_mfma_f32_32x32x16_bf16 v[16:31], v[8:11], v[80:83], v[16:31]
	s_waitcnt lgkmcnt(10)
	v_mfma_f32_32x32x16_bf16 v[32:47], v[12:15], v[84:87], v[32:47]
	s_waitcnt lgkmcnt(8)
	v_mfma_f32_32x32x16_bf16 v[16:31], v[164:167], v[84:87], v[16:31]
	s_waitcnt lgkmcnt(6)
	v_mfma_f32_32x32x16_bf16 v[32:47], v[168:171], v[64:67], v[32:47]
	s_waitcnt lgkmcnt(4)
	v_mfma_f32_32x32x16_bf16 v[16:31], v[172:175], v[64:67], v[16:31]
	s_waitcnt lgkmcnt(2)
	v_mfma_f32_32x32x16_bf16 v[32:47], v[176:179], v[68:71], v[32:47]
	s_waitcnt lgkmcnt(0)
	v_mfma_f32_32x32x16_bf16 v[16:31], v[180:183], v[68:71], v[16:31]
	s_setprio 0
	s_andn2_b64 vcc, exec, s[22:23]
	s_mov_b64 s[16:17], -1
	s_cbranch_vccnz .LBB0_950
	s_lshl_b64 s[16:17], 1, s30
	s_andn2_b64 s[24:25], s[12:13], s[16:17]
	s_mov_b64 s[16:17], 0
	s_waitcnt lgkmcnt(0)
	s_barrier
	s_branch .LBB0_950

.LBB0_997:
	ds_read_b128 v[4:7], v239
	ds_read_b128 v[8:11], v239 offset:32
	ds_read_b128 v[12:15], v239 offset:4608
	ds_read_b128 v[64:67], v239 offset:4640
	ds_read_b128 v[68:71], v239 offset:64
	ds_read_b128 v[72:75], v239 offset:96
	ds_read_b128 v[76:79], v239 offset:4672
	ds_read_b128 v[112:115], v239 offset:4704
	s_cmp_lg_u64 s[12:13], 0
	s_cselect_b64 s[80:81], -1, 0
	s_ff1_i32_b64 s0, s[12:13]
	s_and_b64 s[16:17], s[80:81], exec
	s_cselect_b32 s16, s0, -1
	s_cmp_lt_i32 s16, 0
	s_cbranch_scc1 .LBB0_999
	v_mad_u64_u32 v[0:1], s[16:17], s16, v243, v[228:229]
	global_load_dwordx4 v[148:151], v[0:1], off offset:2048
	global_load_dwordx4 v[152:155], v[0:1], off offset:2304
.LBB0_999:
	s_lshl_b32 s2, s2, 6
	s_setprio 1
	s_waitcnt lgkmcnt(7)
	v_mfma_f32_32x32x16_bf16 v[80:95], v[4:7], v[132:135], v[48:63]
	s_waitcnt lgkmcnt(5)
	v_mfma_f32_32x32x16_bf16 v[96:111], v[12:15], v[132:135], v[48:63]
	s_setprio 0
	v_mfma_f32_32x32x16_bf16 v[80:95], v[8:11], v[136:139], v[80:95]
	ds_read_b64_tr_b16 v[4:5], v235 offset:18432
	ds_read_b64_tr_b16 v[6:7], v235 offset:19968
	ds_read_b64_tr_b16 v[10:11], v235 offset:20032
	ds_read_b64_tr_b16 v[8:9], v235 offset:18496
	ds_read_b64_tr_b16 v[12:13], v235 offset:21504
	ds_read_b64_tr_b16 v[14:15], v235 offset:23040
	ds_read_b64_tr_b16 v[166:167], v235 offset:23104
	ds_read_b64_tr_b16 v[164:165], v235 offset:21568
	ds_read_b64_tr_b16 v[168:169], v235 offset:24576
	ds_read_b64_tr_b16 v[170:171], v235 offset:26112
	ds_read_b64_tr_b16 v[174:175], v235 offset:26176
	ds_read_b64_tr_b16 v[172:173], v235 offset:24640
	ds_read_b64_tr_b16 v[176:177], v235 offset:27648
	ds_read_b64_tr_b16 v[178:179], v235 offset:29184
	ds_read_b64_tr_b16 v[182:183], v235 offset:29248
	ds_read_b64_tr_b16 v[180:181], v235 offset:27712
	s_waitcnt lgkmcnt(14)
	v_mfma_f32_32x32x16_bf16 v[96:111], v[64:67], v[136:139], v[96:111]
	v_mfma_f32_32x32x16_bf16 v[80:95], v[68:71], v[140:143], v[80:95]
	v_mfma_f32_32x32x16_bf16 v[96:111], v[76:79], v[140:143], v[96:111]
	v_mfma_f32_32x32x16_bf16 v[80:95], v[72:75], v[144:147], v[80:95]
	v_mfma_f32_32x32x16_bf16 v[96:111], v[112:115], v[144:147], v[96:111]
	s_or_b32 s16, s2, 63
	v_cmp_ge_i32_e32 vcc, s2, v226
	v_cmp_le_u32_e64 s[16:17], s16, v246
	s_and_b64 s[16:17], vcc, s[16:17]
	s_nop 0
	v_cndmask_b32_e64 v0, 0, 1, s[16:17]
	v_cmp_ne_u32_e32 vcc, 0, v0
	s_cmp_eq_u64 vcc, exec
	s_cbranch_scc1 .LBB0_1003
	v_or_b32_e32 v0, s2, v237
	v_or_b32_e32 v1, 32, v0
	v_cmp_lt_i32_e64 s[18:19], v1, v226
	v_cmp_gt_u32_e64 s[20:21], v1, v246
	s_or_b64 s[18:19], s[18:19], s[20:21]
	v_or_b32_e32 v1, 1, v0
	v_cndmask_b32_e64 v96, v96, v244, s[18:19]
	v_cmp_ge_i32_e64 s[18:19], v1, v226
	v_or_b32_e32 v1, 33, v0
	v_cmp_lt_i32_e64 s[22:23], v1, v226
	v_cmp_gt_u32_e64 s[24:25], v1, v246
	s_or_b64 s[22:23], s[22:23], s[24:25]
	v_or_b32_e32 v1, 2, v0
	v_cndmask_b32_e64 v97, v97, v244, s[22:23]
	v_cmp_ge_i32_e64 s[22:23], v1, v226
	v_cmp_le_u32_e64 s[24:25], v1, v246
	v_or_b32_e32 v1, 34, v0
	v_cmp_lt_i32_e64 s[26:27], v1, v226
	v_cmp_gt_u32_e64 s[28:29], v1, v246
	v_or_b32_e32 v1, s2, v236
	s_or_b64 s[26:27], s[26:27], s[28:29]
	v_or_b32_e32 v3, 3, v1
	v_cndmask_b32_e64 v98, v98, v244, s[26:27]
	v_cmp_ge_i32_e64 s[26:27], v3, v226
	v_cmp_le_u32_e64 s[28:29], v3, v246
	v_or_b32_e32 v3, 35, v1
	v_cmp_lt_i32_e64 s[30:31], v3, v226
	v_cmp_gt_u32_e64 s[34:35], v3, v246
	s_or_b64 s[30:31], s[30:31], s[34:35]
	v_or_b32_e32 v3, 8, v0
	v_cndmask_b32_e64 v99, v99, v244, s[30:31]
	v_cmp_ge_i32_e64 s[30:31], v3, v226
	v_cmp_le_u32_e64 s[34:35], v3, v246
	v_or_b32_e32 v3, 40, v0
	v_cmp_lt_i32_e64 s[36:37], v3, v226
	v_cmp_gt_u32_e64 s[38:39], v3, v246
	s_or_b64 s[36:37], s[36:37], s[38:39]
	v_or_b32_e32 v3, 9, v0
	v_cndmask_b32_e64 v100, v100, v244, s[36:37]
	v_cmp_ge_i32_e64 s[36:37], v3, v226
	v_cmp_le_u32_e64 s[38:39], v3, v246
	v_or_b32_e32 v3, 41, v0
	v_cmp_lt_i32_e64 s[40:41], v3, v226
	v_cmp_gt_u32_e64 s[42:43], v3, v246
	s_or_b64 s[40:41], s[40:41], s[42:43]
	v_or_b32_e32 v3, 10, v0
	v_cndmask_b32_e64 v101, v101, v244, s[40:41]
	v_cmp_ge_i32_e64 s[40:41], v3, v226
	v_cmp_le_u32_e64 s[42:43], v3, v246
	v_or_b32_e32 v3, 42, v0
	v_cmp_lt_i32_e64 s[44:45], v3, v226
	v_cmp_gt_u32_e64 s[46:47], v3, v246
	s_or_b64 s[44:45], s[44:45], s[46:47]
	v_or_b32_e32 v3, 11, v1
	v_cndmask_b32_e64 v102, v102, v244, s[44:45]
	v_cmp_ge_i32_e64 s[44:45], v3, v226
	v_cmp_le_u32_e64 s[46:47], v3, v246
	v_or_b32_e32 v3, 43, v1
	v_cmp_lt_i32_e64 s[48:49], v3, v226
	v_cmp_gt_u32_e64 s[50:51], v3, v246
	s_or_b64 s[48:49], s[48:49], s[50:51]
	v_or_b32_e32 v3, 16, v0
	v_cndmask_b32_e64 v103, v103, v244, s[48:49]
	v_cmp_ge_i32_e64 s[48:49], v3, v226
	v_cmp_le_u32_e64 s[50:51], v3, v246
	v_or_b32_e32 v3, 48, v0
	v_cmp_lt_i32_e64 s[52:53], v3, v226
	v_cmp_gt_u32_e64 s[54:55], v3, v246
	s_or_b64 s[52:53], s[52:53], s[54:55]
	v_or_b32_e32 v3, 17, v0
	v_cndmask_b32_e64 v104, v104, v244, s[52:53]
	v_cmp_ge_i32_e64 s[52:53], v3, v226
	v_cmp_le_u32_e64 s[54:55], v3, v246
	v_or_b32_e32 v3, 49, v0
	v_cmp_lt_i32_e64 s[56:57], v3, v226
	v_cmp_gt_u32_e64 s[58:59], v3, v246
	s_or_b64 s[56:57], s[56:57], s[58:59]
	v_or_b32_e32 v3, 18, v0
	v_cndmask_b32_e64 v105, v105, v244, s[56:57]
	v_cmp_ge_i32_e64 s[56:57], v3, v226
	v_cmp_le_u32_e64 s[58:59], v3, v246
	v_or_b32_e32 v3, 50, v0
	v_cmp_lt_i32_e64 s[60:61], v3, v226
	v_cmp_gt_u32_e64 s[62:63], v3, v246
	s_or_b64 s[60:61], s[60:61], s[62:63]
	v_or_b32_e32 v3, 19, v1
	v_cndmask_b32_e64 v106, v106, v244, s[60:61]
	v_cmp_ge_i32_e64 s[60:61], v3, v226
	v_cmp_le_u32_e64 s[62:63], v3, v246
	v_or_b32_e32 v3, 51, v1
	v_cmp_lt_i32_e64 s[64:65], v3, v226
	v_cmp_gt_u32_e64 s[66:67], v3, v246
	s_or_b64 s[64:65], s[64:65], s[66:67]
	v_or_b32_e32 v3, 24, v0
	v_cndmask_b32_e64 v107, v107, v244, s[64:65]
	v_cmp_ge_i32_e64 s[64:65], v3, v226
	v_cmp_le_u32_e64 s[66:67], v3, v246
	v_or_b32_e32 v3, 56, v0
	v_cmp_lt_i32_e64 s[68:69], v3, v226
	v_cmp_gt_u32_e64 s[70:71], v3, v246
	s_or_b64 s[68:69], s[68:69], s[70:71]
	v_or_b32_e32 v3, 25, v0
	v_cndmask_b32_e64 v108, v108, v244, s[68:69]
	v_cmp_ge_i32_e64 s[68:69], v3, v226
	v_cmp_le_u32_e64 s[70:71], v3, v246
	v_or_b32_e32 v3, 57, v0
	v_cmp_ge_i32_e32 vcc, v0, v226
	v_cmp_le_u32_e64 s[16:17], v0, v246
	v_cmp_lt_u32_e64 s[20:21], v0, v246
	v_cmp_lt_i32_e64 s[72:73], v3, v226
	v_cmp_gt_u32_e64 s[74:75], v3, v246
	v_or_b32_e32 v3, 26, v0
	v_or_b32_e32 v0, 58, v0
	v_cmp_lt_i32_e64 s[76:77], v0, v226
	v_cmp_gt_u32_e64 s[78:79], v0, v246
	s_or_b64 s[76:77], s[76:77], s[78:79]
	v_or_b32_e32 v0, 27, v1
	v_cndmask_b32_e64 v110, v110, v244, s[76:77]
	v_cmp_ge_i32_e64 s[76:77], v0, v226
	v_cmp_le_u32_e64 s[78:79], v0, v246
	v_or_b32_e32 v0, 59, v1
	s_or_b64 s[72:73], s[72:73], s[74:75]
	v_cmp_lt_i32_e64 s[82:83], v0, v226
	v_cmp_gt_u32_e64 s[84:85], v0, v246
	v_cndmask_b32_e64 v109, v109, v244, s[72:73]
	v_cmp_ge_i32_e64 s[72:73], v3, v226
	v_cmp_le_u32_e64 s[74:75], v3, v246
	s_or_b64 s[84:85], s[82:83], s[84:85]
	s_and_saveexec_b64 s[82:83], s[84:85]
	v_mov_b32_e32 v111, s5
	s_or_b64 exec, exec, s[82:83]
	s_and_b64 vcc, vcc, s[16:17]
	v_cndmask_b32_e32 v80, v244, v80, vcc
	s_and_b64 vcc, s[20:21], s[18:19]
	v_cndmask_b32_e32 v81, v244, v81, vcc
	s_and_b64 vcc, s[22:23], s[24:25]
	v_cndmask_b32_e32 v82, v244, v82, vcc
	s_and_b64 vcc, s[26:27], s[28:29]
	v_cndmask_b32_e32 v83, v244, v83, vcc
	s_and_b64 vcc, s[30:31], s[34:35]
	v_cndmask_b32_e32 v84, v244, v84, vcc
	s_and_b64 vcc, s[36:37], s[38:39]
	v_cndmask_b32_e32 v85, v244, v85, vcc
	s_and_b64 vcc, s[40:41], s[42:43]
	v_cndmask_b32_e32 v86, v244, v86, vcc
	s_and_b64 vcc, s[44:45], s[46:47]
	v_cndmask_b32_e32 v87, v244, v87, vcc
	s_and_b64 vcc, s[48:49], s[50:51]
	v_cndmask_b32_e32 v88, v244, v88, vcc
	s_and_b64 vcc, s[52:53], s[54:55]
	v_cndmask_b32_e32 v89, v244, v89, vcc
	s_and_b64 vcc, s[56:57], s[58:59]
	v_cndmask_b32_e32 v90, v244, v90, vcc
	s_and_b64 vcc, s[60:61], s[62:63]
	v_cndmask_b32_e32 v91, v244, v91, vcc
	s_and_b64 vcc, s[64:65], s[66:67]
	v_cndmask_b32_e32 v92, v244, v92, vcc
	s_and_b64 vcc, s[68:69], s[70:71]
	v_cndmask_b32_e32 v93, v244, v93, vcc
	s_and_b64 vcc, s[72:73], s[74:75]
	v_cndmask_b32_e32 v94, v244, v94, vcc
	s_and_b64 vcc, s[76:77], s[78:79]
	v_cndmask_b32_e32 v95, v244, v95, vcc

.LBB0_1010:
	v_exp_f32_e32 v112, v80
	v_exp_f32_e32 v80, v96
	v_exp_f32_e32 v113, v81
	v_exp_f32_e32 v81, v97
	v_exp_f32_e32 v114, v82
	v_exp_f32_e32 v82, v98
	v_exp_f32_e32 v115, v83
	v_exp_f32_e32 v83, v99
	v_exp_f32_e32 v116, v84
	v_exp_f32_e32 v84, v100
	v_exp_f32_e32 v117, v85
	v_exp_f32_e32 v85, v101
	v_exp_f32_e32 v118, v86
	v_exp_f32_e32 v86, v102
	v_exp_f32_e32 v119, v87
	v_exp_f32_e32 v87, v103
	v_exp_f32_e32 v120, v88
	v_exp_f32_e32 v88, v104
	v_exp_f32_e32 v121, v89
	v_exp_f32_e32 v89, v105
	v_exp_f32_e32 v122, v90
	v_exp_f32_e32 v90, v106
	v_exp_f32_e32 v123, v91
	v_exp_f32_e32 v91, v107
	v_exp_f32_e32 v124, v92
	v_exp_f32_e32 v92, v108
	v_exp_f32_e32 v125, v93
	v_exp_f32_e32 v93, v109
	v_exp_f32_e32 v126, v94
	v_exp_f32_e32 v94, v110
	v_exp_f32_e32 v127, v95
	v_exp_f32_e32 v95, v111
	s_mov_b64 s[16:17], -1
	v_add_f32_e32 v0, v112, v80
	v_add_f32_e32 v1, v113, v81
	v_add_f32_e32 v3, v114, v82
	v_add_f32_e32 v96, v115, v83
	v_cvt_pk_bf16_f32 v97, v114, v115
	v_add_f32_e32 v0, v0, v116
	v_add_f32_e32 v1, v1, v117
	v_add_f32_e32 v3, v3, v118
	v_add_f32_e32 v96, v96, v119
	v_cvt_pk_bf16_f32 v98, v116, v117
	v_add_f32_e32 v0, v0, v84
	v_add_f32_e32 v1, v1, v85
	v_add_f32_e32 v3, v3, v86
	v_add_f32_e32 v96, v96, v87
	v_cvt_pk_bf16_f32 v99, v118, v119
	v_add_f32_e32 v0, v0, v120
	v_add_f32_e32 v1, v1, v121
	v_add_f32_e32 v3, v3, v122
	v_add_f32_e32 v96, v96, v123
	v_cvt_pk_bf16_f32 v100, v120, v121
	v_add_f32_e32 v0, v0, v88
	v_add_f32_e32 v1, v1, v89
	v_add_f32_e32 v3, v3, v90
	v_add_f32_e32 v96, v96, v91
	v_cvt_pk_bf16_f32 v101, v122, v123
	v_add_f32_e32 v0, v0, v124
	v_add_f32_e32 v1, v1, v125
	v_add_f32_e32 v3, v3, v126
	v_add_f32_e32 v96, v96, v127
	v_cvt_pk_bf16_f32 v102, v124, v125
	v_add_f32_e32 v0, v0, v92
	v_add_f32_e32 v1, v1, v93
	v_add_f32_e32 v3, v3, v94
	v_add_f32_e32 v96, v96, v95
	v_cvt_pk_bf16_f32 v103, v126, v127
	v_add_f32_e32 v0, v0, v1
	v_add_f32_e32 v1, v3, v96
	v_cvt_pk_bf16_f32 v96, v112, v113
	v_add_f32_e32 v0, v0, v1
	v_cvt_pk_bf16_f32 v80, v80, v81
	v_add_f32_e32 v222, v222, v0
	v_cvt_pk_bf16_f32 v81, v82, v83
	v_cvt_pk_bf16_f32 v82, v84, v85
	v_cvt_pk_bf16_f32 v83, v86, v87
	v_cvt_pk_bf16_f32 v84, v88, v89
	v_cvt_pk_bf16_f32 v85, v90, v91
	v_cvt_pk_bf16_f32 v86, v92, v93
	v_cvt_pk_bf16_f32 v87, v94, v95
	s_waitcnt vmcnt(1)
	ds_write_b128 v192, v[156:159] offset:9216
	s_waitcnt vmcnt(0)
	ds_write_b128 v194, v[160:163] offset:30720
	s_setprio 1
	v_mfma_f32_32x32x16_bf16 v[32:47], v[4:7], v[96:99], v[32:47]
	s_waitcnt lgkmcnt(12)
	v_mfma_f32_32x32x16_bf16 v[16:31], v[8:11], v[96:99], v[16:31]
	s_waitcnt lgkmcnt(10)
	v_mfma_f32_32x32x16_bf16 v[32:47], v[12:15], v[100:103], v[32:47]
	s_waitcnt lgkmcnt(8)
	v_mfma_f32_32x32x16_bf16 v[16:31], v[164:167], v[100:103], v[16:31]
	s_waitcnt lgkmcnt(6)
	v_mfma_f32_32x32x16_bf16 v[32:47], v[168:171], v[80:83], v[32:47]
	s_waitcnt lgkmcnt(4)
	v_mfma_f32_32x32x16_bf16 v[16:31], v[172:175], v[80:83], v[16:31]
	s_waitcnt lgkmcnt(2)
	v_mfma_f32_32x32x16_bf16 v[32:47], v[176:179], v[84:87], v[32:47]
	s_waitcnt lgkmcnt(0)
	v_mfma_f32_32x32x16_bf16 v[16:31], v[180:183], v[84:87], v[16:31]
	s_setprio 0
	s_cmp_lt_i32 s33, 0
	s_cbranch_scc1 .LBB0_1025
	s_lshl_b64 s[16:17], 1, s0
	s_andn2_b64 s[86:87], s[12:13], s[16:17]
	s_ff1_i32_b64 s96, s[86:87]
	s_cmp_lg_u64 s[86:87], 0
	s_cselect_b32 s2, s96, -1
	s_cmp_lt_i32 s2, 0
	s_waitcnt lgkmcnt(0)
	s_barrier
	ds_read_b128 v[4:7], v239 offset:9216
	ds_read_b128 v[8:11], v239 offset:9248
	ds_read_b128 v[12:15], v239 offset:13824
	ds_read_b128 v[96:99], v239 offset:13856
	ds_read_b128 v[100:103], v239 offset:9280
	ds_read_b128 v[104:107], v239 offset:9312
	ds_read_b128 v[108:111], v239 offset:13888
	ds_read_b128 v[116:119], v239 offset:13920
	s_cbranch_scc1 .LBB0_1013
	v_mad_u64_u32 v[0:1], s[12:13], s2, v243, v[228:229]
	global_load_dwordx4 v[156:159], v[0:1], off offset:2048
	global_load_dwordx4 v[160:163], v[0:1], off offset:2304
.LBB0_1013:
	s_lshl_b32 s12, s33, 6
	s_setprio 1
	s_waitcnt lgkmcnt(7)
	v_mfma_f32_32x32x16_bf16 v[80:95], v[4:7], v[132:135], v[64:79]
	s_waitcnt lgkmcnt(5)
	v_mfma_f32_32x32x16_bf16 v[64:79], v[12:15], v[132:135], v[64:79]
	s_setprio 0
	v_mfma_f32_32x32x16_bf16 v[80:95], v[8:11], v[136:139], v[80:95]
	s_waitcnt lgkmcnt(4)
	v_mfma_f32_32x32x16_bf16 v[64:79], v[96:99], v[136:139], v[64:79]
	ds_read_b64_tr_b16 v[4:5], v235 offset:30720
	ds_read_b64_tr_b16 v[6:7], v235 offset:32256
	ds_read_b64_tr_b16 v[10:11], v235 offset:32320
	ds_read_b64_tr_b16 v[8:9], v235 offset:30784
	ds_read_b64_tr_b16 v[12:13], v235 offset:33792
	ds_read_b64_tr_b16 v[14:15], v235 offset:35328
	ds_read_b64_tr_b16 v[98:99], v235 offset:35392
	ds_read_b64_tr_b16 v[96:97], v235 offset:33856
	s_waitcnt lgkmcnt(11)
	v_mfma_f32_32x32x16_bf16 v[80:95], v[100:103], v[140:143], v[80:95]
	s_waitcnt lgkmcnt(9)
	v_mfma_f32_32x32x16_bf16 v[64:79], v[108:111], v[140:143], v[64:79]
	v_mfma_f32_32x32x16_bf16 v[80:95], v[104:107], v[144:147], v[80:95]
	ds_read_b64_tr_b16 v[100:101], v235 offset:36864
	ds_read_b64_tr_b16 v[102:103], v235 offset:38400
	ds_read_b64_tr_b16 v[106:107], v235 offset:38464
	ds_read_b64_tr_b16 v[104:105], v235 offset:36928
	ds_read_b64_tr_b16 v[108:109], v235 offset:39936
	ds_read_b64_tr_b16 v[110:111], v235 offset:41472
	ds_read_b64_tr_b16 v[114:115], v235 offset:41536
	ds_read_b64_tr_b16 v[112:113], v235 offset:40000
	s_waitcnt lgkmcnt(14)
	v_mfma_f32_32x32x16_bf16 v[64:79], v[116:119], v[144:147], v[64:79]
	s_or_b32 s13, s12, 63
	v_cmp_ge_i32_e32 vcc, s12, v226
	v_cmp_le_u32_e64 s[16:17], s13, v246
	s_and_b64 s[16:17], vcc, s[16:17]
	s_nop 0
	v_cndmask_b32_e64 v0, 0, 1, s[16:17]
	v_cmp_ne_u32_e32 vcc, 0, v0
	s_cmp_eq_u64 vcc, exec
	s_cbranch_scc1 .LBB0_1017
	v_or_b32_e32 v0, s12, v237
	v_or_b32_e32 v1, 32, v0
	v_cmp_lt_i32_e64 s[18:19], v1, v226
	v_cmp_gt_u32_e64 s[20:21], v1, v246
	s_or_b64 s[18:19], s[18:19], s[20:21]
	v_or_b32_e32 v1, 1, v0
	v_cndmask_b32_e64 v64, v64, v244, s[18:19]
	v_cmp_ge_i32_e64 s[18:19], v1, v226
	v_or_b32_e32 v1, 33, v0
	v_cmp_lt_i32_e64 s[22:23], v1, v226
	v_cmp_gt_u32_e64 s[24:25], v1, v246
	s_or_b64 s[22:23], s[22:23], s[24:25]
	v_or_b32_e32 v1, 2, v0
	v_cndmask_b32_e64 v65, v65, v244, s[22:23]
	v_cmp_ge_i32_e64 s[22:23], v1, v226
	v_cmp_le_u32_e64 s[24:25], v1, v246
	v_or_b32_e32 v1, 34, v0
	v_cmp_lt_i32_e64 s[26:27], v1, v226
	v_cmp_gt_u32_e64 s[28:29], v1, v246
	v_or_b32_e32 v1, s12, v236
	s_or_b64 s[26:27], s[26:27], s[28:29]
	v_or_b32_e32 v3, 3, v1
	v_cndmask_b32_e64 v66, v66, v244, s[26:27]
	v_cmp_ge_i32_e64 s[26:27], v3, v226
	v_cmp_le_u32_e64 s[28:29], v3, v246
	v_or_b32_e32 v3, 35, v1
	v_cmp_lt_i32_e64 s[30:31], v3, v226
	v_cmp_gt_u32_e64 s[34:35], v3, v246
	s_or_b64 s[30:31], s[30:31], s[34:35]
	v_or_b32_e32 v3, 8, v0
	v_cndmask_b32_e64 v67, v67, v244, s[30:31]
	v_cmp_ge_i32_e64 s[30:31], v3, v226
	v_cmp_le_u32_e64 s[34:35], v3, v246
	v_or_b32_e32 v3, 40, v0
	v_cmp_lt_i32_e64 s[36:37], v3, v226
	v_cmp_gt_u32_e64 s[38:39], v3, v246
	s_or_b64 s[36:37], s[36:37], s[38:39]
	v_or_b32_e32 v3, 9, v0
	v_cndmask_b32_e64 v68, v68, v244, s[36:37]
	v_cmp_ge_i32_e64 s[36:37], v3, v226
	v_cmp_le_u32_e64 s[38:39], v3, v246
	v_or_b32_e32 v3, 41, v0
	v_cmp_lt_i32_e64 s[40:41], v3, v226
	v_cmp_gt_u32_e64 s[42:43], v3, v246
	s_or_b64 s[40:41], s[40:41], s[42:43]
	v_or_b32_e32 v3, 10, v0
	v_cndmask_b32_e64 v69, v69, v244, s[40:41]
	v_cmp_ge_i32_e64 s[40:41], v3, v226
	v_cmp_le_u32_e64 s[42:43], v3, v246
	v_or_b32_e32 v3, 42, v0
	v_cmp_lt_i32_e64 s[44:45], v3, v226
	v_cmp_gt_u32_e64 s[46:47], v3, v246
	s_or_b64 s[44:45], s[44:45], s[46:47]
	v_or_b32_e32 v3, 11, v1
	v_cndmask_b32_e64 v70, v70, v244, s[44:45]
	v_cmp_ge_i32_e64 s[44:45], v3, v226
	v_cmp_le_u32_e64 s[46:47], v3, v246
	v_or_b32_e32 v3, 43, v1
	v_cmp_lt_i32_e64 s[48:49], v3, v226
	v_cmp_gt_u32_e64 s[50:51], v3, v246
	s_or_b64 s[48:49], s[48:49], s[50:51]
	v_or_b32_e32 v3, 16, v0
	v_cndmask_b32_e64 v71, v71, v244, s[48:49]
	v_cmp_ge_i32_e64 s[48:49], v3, v226
	v_cmp_le_u32_e64 s[50:51], v3, v246
	v_or_b32_e32 v3, 48, v0
	v_cmp_lt_i32_e64 s[52:53], v3, v226
	v_cmp_gt_u32_e64 s[54:55], v3, v246
	s_or_b64 s[52:53], s[52:53], s[54:55]
	v_or_b32_e32 v3, 17, v0
	v_cndmask_b32_e64 v72, v72, v244, s[52:53]
	v_cmp_ge_i32_e64 s[52:53], v3, v226
	v_cmp_le_u32_e64 s[54:55], v3, v246
	v_or_b32_e32 v3, 49, v0
	v_cmp_lt_i32_e64 s[56:57], v3, v226
	v_cmp_gt_u32_e64 s[58:59], v3, v246
	s_or_b64 s[56:57], s[56:57], s[58:59]
	v_or_b32_e32 v3, 18, v0
	v_cndmask_b32_e64 v73, v73, v244, s[56:57]
	v_cmp_ge_i32_e64 s[56:57], v3, v226
	v_cmp_le_u32_e64 s[58:59], v3, v246
	v_or_b32_e32 v3, 50, v0
	v_cmp_lt_i32_e64 s[60:61], v3, v226
	v_cmp_gt_u32_e64 s[62:63], v3, v246
	s_or_b64 s[60:61], s[60:61], s[62:63]
	v_or_b32_e32 v3, 19, v1
	v_cndmask_b32_e64 v74, v74, v244, s[60:61]
	v_cmp_ge_i32_e64 s[60:61], v3, v226
	v_cmp_le_u32_e64 s[62:63], v3, v246
	v_or_b32_e32 v3, 51, v1
	v_cmp_lt_i32_e64 s[64:65], v3, v226
	v_cmp_gt_u32_e64 s[66:67], v3, v246
	s_or_b64 s[64:65], s[64:65], s[66:67]
	v_or_b32_e32 v3, 24, v0
	v_cndmask_b32_e64 v75, v75, v244, s[64:65]
	v_cmp_ge_i32_e64 s[64:65], v3, v226
	v_cmp_le_u32_e64 s[66:67], v3, v246
	v_or_b32_e32 v3, 56, v0
	v_cmp_lt_i32_e64 s[68:69], v3, v226
	v_cmp_gt_u32_e64 s[70:71], v3, v246
	s_or_b64 s[68:69], s[68:69], s[70:71]
	v_or_b32_e32 v3, 25, v0
	v_cndmask_b32_e64 v76, v76, v244, s[68:69]
	v_cmp_ge_i32_e64 s[68:69], v3, v226
	v_cmp_le_u32_e64 s[70:71], v3, v246
	v_or_b32_e32 v3, 57, v0
	v_cmp_ge_i32_e32 vcc, v0, v226
	v_cmp_le_u32_e64 s[16:17], v0, v246
	v_cmp_lt_u32_e64 s[20:21], v0, v246
	v_cmp_lt_i32_e64 s[72:73], v3, v226
	v_cmp_gt_u32_e64 s[74:75], v3, v246
	v_or_b32_e32 v3, 26, v0
	v_or_b32_e32 v0, 58, v0
	v_cmp_lt_i32_e64 s[76:77], v0, v226
	v_cmp_gt_u32_e64 s[78:79], v0, v246
	s_or_b64 s[76:77], s[76:77], s[78:79]
	v_or_b32_e32 v0, 27, v1
	v_cndmask_b32_e64 v78, v78, v244, s[76:77]
	v_cmp_ge_i32_e64 s[76:77], v0, v226
	v_cmp_le_u32_e64 s[78:79], v0, v246
	v_or_b32_e32 v0, 59, v1
	s_or_b64 s[72:73], s[72:73], s[74:75]
	v_cmp_lt_i32_e64 s[82:83], v0, v226
	v_cmp_gt_u32_e64 s[84:85], v0, v246
	v_cndmask_b32_e64 v77, v77, v244, s[72:73]
	v_cmp_ge_i32_e64 s[72:73], v3, v226
	v_cmp_le_u32_e64 s[74:75], v3, v246
	s_or_b64 s[82:83], s[82:83], s[84:85]
	s_and_saveexec_b64 s[12:13], s[82:83]
	v_mov_b32_e32 v79, s5
	s_or_b64 exec, exec, s[12:13]
	s_and_b64 vcc, vcc, s[16:17]
	v_cndmask_b32_e32 v80, v244, v80, vcc
	s_and_b64 vcc, s[20:21], s[18:19]
	v_cndmask_b32_e32 v81, v244, v81, vcc
	s_and_b64 vcc, s[22:23], s[24:25]
	v_cndmask_b32_e32 v82, v244, v82, vcc
	s_and_b64 vcc, s[26:27], s[28:29]
	v_cndmask_b32_e32 v83, v244, v83, vcc
	s_and_b64 vcc, s[30:31], s[34:35]
	v_cndmask_b32_e32 v84, v244, v84, vcc
	s_and_b64 vcc, s[36:37], s[38:39]
	v_cndmask_b32_e32 v85, v244, v85, vcc
	s_and_b64 vcc, s[40:41], s[42:43]
	v_cndmask_b32_e32 v86, v244, v86, vcc
	s_and_b64 vcc, s[44:45], s[46:47]
	v_cndmask_b32_e32 v87, v244, v87, vcc
	s_and_b64 vcc, s[48:49], s[50:51]
	v_cndmask_b32_e32 v88, v244, v88, vcc
	s_and_b64 vcc, s[52:53], s[54:55]
	v_cndmask_b32_e32 v89, v244, v89, vcc
	s_and_b64 vcc, s[56:57], s[58:59]
	v_cndmask_b32_e32 v90, v244, v90, vcc
	s_and_b64 vcc, s[60:61], s[62:63]
	v_cndmask_b32_e32 v91, v244, v91, vcc
	s_and_b64 vcc, s[64:65], s[66:67]
	v_cndmask_b32_e32 v92, v244, v92, vcc
	s_and_b64 vcc, s[68:69], s[70:71]
	v_cndmask_b32_e32 v93, v244, v93, vcc
	s_and_b64 vcc, s[72:73], s[74:75]
	v_cndmask_b32_e32 v94, v244, v94, vcc
	s_and_b64 vcc, s[76:77], s[78:79]
	v_cndmask_b32_e32 v95, v244, v95, vcc

.LBB0_1023:
	v_exp_f32_e32 v80, v80
	v_exp_f32_e32 v64, v64
	v_exp_f32_e32 v81, v81
	v_exp_f32_e32 v65, v65
	v_exp_f32_e32 v82, v82
	v_exp_f32_e32 v66, v66
	v_exp_f32_e32 v83, v83
	v_exp_f32_e32 v67, v67
	v_exp_f32_e32 v84, v84
	v_exp_f32_e32 v68, v68
	v_exp_f32_e32 v85, v85
	v_exp_f32_e32 v69, v69
	v_exp_f32_e32 v86, v86
	v_exp_f32_e32 v70, v70
	v_exp_f32_e32 v87, v87
	v_exp_f32_e32 v71, v71
	v_exp_f32_e32 v88, v88
	v_exp_f32_e32 v72, v72
	v_exp_f32_e32 v89, v89
	v_exp_f32_e32 v73, v73
	v_exp_f32_e32 v90, v90
	v_exp_f32_e32 v74, v74
	v_exp_f32_e32 v91, v91
	v_exp_f32_e32 v75, v75
	v_exp_f32_e32 v92, v92
	v_exp_f32_e32 v76, v76
	v_exp_f32_e32 v93, v93
	v_exp_f32_e32 v77, v77
	v_exp_f32_e32 v94, v94
	v_exp_f32_e32 v78, v78
	v_exp_f32_e32 v95, v95
	v_exp_f32_e32 v79, v79
	v_add_f32_e32 v0, v80, v64
	v_add_f32_e32 v1, v81, v65
	v_add_f32_e32 v3, v82, v66
	v_add_f32_e32 v116, v83, v67
	v_cvt_pk_bf16_f32 v80, v80, v81
	v_add_f32_e32 v0, v0, v84
	v_add_f32_e32 v1, v1, v85
	v_add_f32_e32 v3, v3, v86
	v_add_f32_e32 v116, v116, v87
	v_cvt_pk_bf16_f32 v81, v82, v83
	v_add_f32_e32 v0, v0, v68
	v_add_f32_e32 v1, v1, v69
	v_add_f32_e32 v3, v3, v70
	v_add_f32_e32 v116, v116, v71
	v_cvt_pk_bf16_f32 v82, v84, v85
	v_add_f32_e32 v0, v0, v88
	v_add_f32_e32 v1, v1, v89
	v_add_f32_e32 v3, v3, v90
	v_add_f32_e32 v116, v116, v91
	v_cvt_pk_bf16_f32 v83, v86, v87
	v_add_f32_e32 v0, v0, v72
	v_add_f32_e32 v1, v1, v73
	v_add_f32_e32 v3, v3, v74
	v_add_f32_e32 v116, v116, v75
	v_cvt_pk_bf16_f32 v84, v88, v89
	v_add_f32_e32 v0, v0, v92
	v_add_f32_e32 v1, v1, v93
	v_add_f32_e32 v3, v3, v94
	v_add_f32_e32 v116, v116, v95
	v_cvt_pk_bf16_f32 v85, v90, v91
	v_add_f32_e32 v0, v0, v76
	v_add_f32_e32 v1, v1, v77
	v_add_f32_e32 v3, v3, v78
	v_add_f32_e32 v116, v116, v79
	v_cvt_pk_bf16_f32 v86, v92, v93
	v_add_f32_e32 v0, v0, v1
	v_add_f32_e32 v1, v3, v116
	v_cvt_pk_bf16_f32 v87, v94, v95
	v_add_f32_e32 v0, v0, v1
	v_cvt_pk_bf16_f32 v64, v64, v65
	v_cvt_pk_bf16_f32 v65, v66, v67
	v_cvt_pk_bf16_f32 v66, v68, v69
	v_cvt_pk_bf16_f32 v67, v70, v71
	v_cvt_pk_bf16_f32 v68, v72, v73
	v_cvt_pk_bf16_f32 v69, v74, v75
	v_cvt_pk_bf16_f32 v70, v76, v77
	v_cvt_pk_bf16_f32 v71, v78, v79
	s_waitcnt vmcnt(1)
	ds_write_b128 v192, v[148:151]
	s_waitcnt vmcnt(0)
	ds_write_b128 v194, v[152:155] offset:18432
	s_setprio 1
	v_mfma_f32_32x32x16_bf16 v[32:47], v[4:7], v[80:83], v[32:47]
	s_waitcnt lgkmcnt(12)
	v_mfma_f32_32x32x16_bf16 v[16:31], v[8:11], v[80:83], v[16:31]
	s_waitcnt lgkmcnt(10)
	v_mfma_f32_32x32x16_bf16 v[32:47], v[12:15], v[84:87], v[32:47]
	s_waitcnt lgkmcnt(8)
	v_mfma_f32_32x32x16_bf16 v[16:31], v[96:99], v[84:87], v[16:31]
	s_waitcnt lgkmcnt(6)
	v_mfma_f32_32x32x16_bf16 v[32:47], v[100:103], v[64:67], v[32:47]
	s_waitcnt lgkmcnt(4)
	v_mfma_f32_32x32x16_bf16 v[16:31], v[104:107], v[64:67], v[16:31]
	s_waitcnt lgkmcnt(2)
	v_mfma_f32_32x32x16_bf16 v[32:47], v[108:111], v[68:71], v[32:47]
	s_waitcnt lgkmcnt(0)
	v_mfma_f32_32x32x16_bf16 v[16:31], v[112:115], v[68:71], v[16:31]
	s_setprio 0
	s_andn2_b64 vcc, exec, s[80:81]
	s_mov_b64 s[16:17], -1
	s_cbranch_vccnz .LBB0_996
	s_lshl_b64 s[12:13], 1, s96
	s_andn2_b64 s[12:13], s[86:87], s[12:13]
	s_mov_b64 s[16:17], 0
	s_waitcnt lgkmcnt(0)
	s_barrier
	s_branch .LBB0_996
